# v31 + E_raw (ER) tile stores non-temporal in the P2 E GEMM epilogue (keep 32 MiB out of the full LLC; P6 prefetches its own tile at its cu_wait)
# speedup vs baseline: 1.0032x; 1.0032x over previous
.LBB0_376:
	v_lshl_add_u32 v144, s10, 8, v153
	v_mul_f32_e32 v162, v127, v127
	v_mul_f32_e32 v163, v129, v129
	v_ashrrev_i32_e32 v145, 31, v144
	v_fmac_f32_e32 v162, v126, v126
	v_fmac_f32_e32 v163, v128, v128
	v_lshl_or_b32 v138, s33, 8, v154
	v_lshlrev_b64 v[160:161], 11, v[144:145]
	v_add_f32_e32 v162, v162, v163
	v_mul_f32_e32 v163, v123, v123
	v_mul_f32_e32 v164, v125, v125
	v_fmac_f32_e32 v163, v122, v122
	v_fmac_f32_e32 v164, v124, v124
	v_cvt_pk_bf16_f32 v126, v126, v127
	v_cvt_pk_bf16_f32 v127, v128, v129
	v_cvt_pk_bf16_f32 v128, v122, v123
	v_cvt_pk_bf16_f32 v129, v124, v125
	v_lshl_add_u64 v[122:123], s[82:83], 0, v[160:161]
	v_lshlrev_b32_e32 v138, 1, v138
	v_mul_f32_e32 v124, v119, v119
	v_mul_f32_e32 v125, v121, v121
	v_lshl_add_u64 v[122:123], v[122:123], 0, v[138:139]
	v_fmac_f32_e32 v124, v118, v118
	v_fmac_f32_e32 v125, v120, v120
	global_store_dwordx4 v[122:123], v[126:129], off nt
	v_add_f32_e32 v124, v124, v125
	v_mul_f32_e32 v125, v115, v115
	v_mul_f32_e32 v126, v117, v117
	v_fmac_f32_e32 v125, v114, v114
	v_fmac_f32_e32 v126, v116, v116
	v_add_f32_e32 v163, v163, v164
	v_add_f32_e32 v125, v125, v126
	v_add_f32_e32 v162, v163, v162
	v_add_f32_e32 v124, v125, v124
	v_add_f32_e32 v124, v124, v162
	v_cvt_pk_bf16_f32 v118, v118, v119
	v_cvt_pk_bf16_f32 v119, v120, v121
	v_cvt_pk_bf16_f32 v120, v114, v115
	v_mov_b32_e32 v114, v124
	s_nop 1
	v_permlane16_swap_b32_e32 v124, v114
	v_add_f32_e32 v114, v124, v114
	v_mov_b32_e32 v115, v114
	s_nop 1
	v_permlane32_swap_b32_e32 v114, v115
	v_cvt_pk_bf16_f32 v121, v116, v117
	global_store_dwordx4 v[122:123], v[118:121], off offset:256 nt
	s_and_saveexec_b64 s[34:35], s[2:3]
	s_cbranch_execz .LBB0_378
	v_add_f32_e32 v116, v114, v115
	v_lshlrev_b64 v[114:115], 6, v[144:145]
	s_lshl_b32 s10, s33, 2
	v_lshl_add_u64 v[114:115], s[20:21], 0, v[114:115]
	v_lshl_add_u64 v[114:115], s[10:11], 2, v[114:115]
	s_lshl_b32 s10, s43, 2
	v_lshl_add_u64 v[114:115], v[114:115], 0, s[10:11]
	global_store_dword v[114:115], v116, off
.LBB0_378:
	s_or_b64 exec, exec, s[34:35]
	v_or_b32_e32 v114, 16, v144
	v_mul_f32_e32 v118, v111, v111
	v_mul_f32_e32 v119, v113, v113
	v_ashrrev_i32_e32 v115, 31, v114
	v_fmac_f32_e32 v118, v110, v110
	v_fmac_f32_e32 v119, v112, v112
	v_lshlrev_b64 v[116:117], 11, v[114:115]
	v_add_f32_e32 v118, v118, v119
	v_mul_f32_e32 v119, v107, v107
	v_mul_f32_e32 v120, v109, v109
	v_fmac_f32_e32 v119, v106, v106
	v_fmac_f32_e32 v120, v108, v108
	v_cvt_pk_bf16_f32 v110, v110, v111
	v_cvt_pk_bf16_f32 v111, v112, v113
	v_cvt_pk_bf16_f32 v112, v106, v107
	v_cvt_pk_bf16_f32 v113, v108, v109
	v_lshl_add_u64 v[106:107], s[82:83], 0, v[116:117]
	v_mul_f32_e32 v108, v103, v103
	v_mul_f32_e32 v109, v105, v105
	v_lshl_add_u64 v[106:107], v[106:107], 0, v[138:139]
	v_fmac_f32_e32 v108, v102, v102
	v_fmac_f32_e32 v109, v104, v104
	global_store_dwordx4 v[106:107], v[110:113], off nt
	v_add_f32_e32 v108, v108, v109
	v_mul_f32_e32 v109, v99, v99
	v_mul_f32_e32 v110, v101, v101
	v_fmac_f32_e32 v109, v98, v98
	v_fmac_f32_e32 v110, v100, v100
	v_add_f32_e32 v119, v119, v120
	v_add_f32_e32 v109, v109, v110
	v_add_f32_e32 v118, v119, v118
	v_add_f32_e32 v108, v109, v108
	v_add_f32_e32 v108, v108, v118
	v_cvt_pk_bf16_f32 v102, v102, v103
	v_cvt_pk_bf16_f32 v103, v104, v105
	v_cvt_pk_bf16_f32 v104, v98, v99
	v_mov_b32_e32 v98, v108
	s_nop 1
	v_permlane16_swap_b32_e32 v108, v98
	v_add_f32_e32 v98, v108, v98
	v_mov_b32_e32 v99, v98
	s_nop 1
	v_permlane32_swap_b32_e32 v98, v99
	v_cvt_pk_bf16_f32 v105, v100, v101
	global_store_dwordx4 v[106:107], v[102:105], off offset:256 nt
	s_and_saveexec_b64 s[34:35], s[2:3]
	s_cbranch_execz .LBB0_380
	v_add_f32_e32 v100, v98, v99
	v_lshlrev_b64 v[98:99], 6, v[114:115]
	s_lshl_b32 s10, s33, 2
	v_lshl_add_u64 v[98:99], s[20:21], 0, v[98:99]
	v_lshl_add_u64 v[98:99], s[10:11], 2, v[98:99]
	s_lshl_b32 s10, s43, 2
	v_lshl_add_u64 v[98:99], v[98:99], 0, s[10:11]
	global_store_dword v[98:99], v100, off
.LBB0_380:
	s_or_b64 exec, exec, s[34:35]
	v_or_b32_e32 v98, 32, v144
	v_mul_f32_e32 v102, v95, v95
	v_mul_f32_e32 v103, v97, v97
	v_ashrrev_i32_e32 v99, 31, v98
	v_fmac_f32_e32 v102, v94, v94
	v_fmac_f32_e32 v103, v96, v96
	v_lshlrev_b64 v[100:101], 11, v[98:99]
	v_add_f32_e32 v102, v102, v103
	v_mul_f32_e32 v103, v91, v91
	v_mul_f32_e32 v104, v93, v93
	v_fmac_f32_e32 v103, v90, v90
	v_fmac_f32_e32 v104, v92, v92
	v_cvt_pk_bf16_f32 v94, v94, v95
	v_cvt_pk_bf16_f32 v95, v96, v97
	v_cvt_pk_bf16_f32 v96, v90, v91
	v_cvt_pk_bf16_f32 v97, v92, v93
	v_lshl_add_u64 v[90:91], s[82:83], 0, v[100:101]
	v_mul_f32_e32 v92, v87, v87
	v_mul_f32_e32 v93, v89, v89
	v_lshl_add_u64 v[90:91], v[90:91], 0, v[138:139]
	v_fmac_f32_e32 v92, v86, v86
	v_fmac_f32_e32 v93, v88, v88
	global_store_dwordx4 v[90:91], v[94:97], off nt
	v_add_f32_e32 v92, v92, v93
	v_mul_f32_e32 v93, v83, v83
	v_mul_f32_e32 v94, v85, v85
	v_fmac_f32_e32 v93, v82, v82
	v_fmac_f32_e32 v94, v84, v84
	v_add_f32_e32 v103, v103, v104
	v_add_f32_e32 v93, v93, v94
	v_add_f32_e32 v102, v103, v102
	v_add_f32_e32 v92, v93, v92
	v_add_f32_e32 v92, v92, v102
	v_cvt_pk_bf16_f32 v86, v86, v87
	v_cvt_pk_bf16_f32 v87, v88, v89
	v_cvt_pk_bf16_f32 v88, v82, v83
	v_mov_b32_e32 v82, v92
	s_nop 1
	v_permlane16_swap_b32_e32 v92, v82
	v_add_f32_e32 v82, v92, v82
	v_mov_b32_e32 v83, v82
	s_nop 1
	v_permlane32_swap_b32_e32 v82, v83
	v_cvt_pk_bf16_f32 v89, v84, v85
	global_store_dwordx4 v[90:91], v[86:89], off offset:256 nt
	s_and_saveexec_b64 s[34:35], s[2:3]
	s_cbranch_execz .LBB0_382
	v_add_f32_e32 v84, v82, v83
	v_lshlrev_b64 v[82:83], 6, v[98:99]
	s_lshl_b32 s10, s33, 2
	v_lshl_add_u64 v[82:83], s[20:21], 0, v[82:83]
	v_lshl_add_u64 v[82:83], s[10:11], 2, v[82:83]
	s_lshl_b32 s10, s43, 2
	v_lshl_add_u64 v[82:83], v[82:83], 0, s[10:11]
	global_store_dword v[82:83], v84, off
.LBB0_382:
	s_or_b64 exec, exec, s[34:35]
	v_or_b32_e32 v82, 48, v144
	v_mul_f32_e32 v86, v79, v79
	v_mul_f32_e32 v87, v81, v81
	v_ashrrev_i32_e32 v83, 31, v82
	v_fmac_f32_e32 v86, v78, v78
	v_fmac_f32_e32 v87, v80, v80
	v_lshlrev_b64 v[84:85], 11, v[82:83]
	v_add_f32_e32 v86, v86, v87
	v_mul_f32_e32 v87, v75, v75
	v_mul_f32_e32 v88, v77, v77
	v_fmac_f32_e32 v87, v74, v74
	v_fmac_f32_e32 v88, v76, v76
	v_cvt_pk_bf16_f32 v78, v78, v79
	v_cvt_pk_bf16_f32 v79, v80, v81
	v_cvt_pk_bf16_f32 v80, v74, v75
	v_cvt_pk_bf16_f32 v81, v76, v77
	v_lshl_add_u64 v[74:75], s[82:83], 0, v[84:85]
	v_mul_f32_e32 v76, v71, v71
	v_mul_f32_e32 v77, v73, v73
	v_lshl_add_u64 v[74:75], v[74:75], 0, v[138:139]
	v_fmac_f32_e32 v76, v70, v70
	v_fmac_f32_e32 v77, v72, v72
	global_store_dwordx4 v[74:75], v[78:81], off nt
	v_add_f32_e32 v76, v76, v77
	v_mul_f32_e32 v77, v67, v67
	v_mul_f32_e32 v78, v69, v69
	v_fmac_f32_e32 v77, v66, v66
	v_fmac_f32_e32 v78, v68, v68
	v_add_f32_e32 v87, v87, v88
	v_add_f32_e32 v77, v77, v78
	v_add_f32_e32 v86, v87, v86
	v_add_f32_e32 v76, v77, v76
	v_add_f32_e32 v76, v76, v86
	v_cvt_pk_bf16_f32 v70, v70, v71
	v_cvt_pk_bf16_f32 v71, v72, v73
	v_cvt_pk_bf16_f32 v72, v66, v67
	v_mov_b32_e32 v66, v76
	s_nop 1
	v_permlane16_swap_b32_e32 v76, v66
	v_add_f32_e32 v66, v76, v66
	v_mov_b32_e32 v67, v66
	s_nop 1
	v_permlane32_swap_b32_e32 v66, v67
	v_cvt_pk_bf16_f32 v73, v68, v69
	global_store_dwordx4 v[74:75], v[70:73], off offset:256 nt
	s_and_saveexec_b64 s[34:35], s[2:3]
	s_cbranch_execz .LBB0_384
	v_add_f32_e32 v68, v66, v67
	v_lshlrev_b64 v[66:67], 6, v[82:83]
	s_lshl_b32 s10, s33, 2
	v_lshl_add_u64 v[66:67], s[20:21], 0, v[66:67]
	v_lshl_add_u64 v[66:67], s[10:11], 2, v[66:67]
	s_lshl_b32 s10, s43, 2
	v_lshl_add_u64 v[66:67], v[66:67], 0, s[10:11]
	global_store_dword v[66:67], v68, off
.LBB0_384:
	s_or_b64 exec, exec, s[34:35]
	v_add_u32_e32 v66, 0x80, v144
	v_mul_f32_e32 v70, v63, v63
	v_mul_f32_e32 v71, v65, v65
	v_ashrrev_i32_e32 v67, 31, v66
	v_fmac_f32_e32 v70, v62, v62
	v_fmac_f32_e32 v71, v64, v64
	v_lshlrev_b64 v[68:69], 11, v[66:67]
	v_add_f32_e32 v70, v70, v71
	v_mul_f32_e32 v71, v59, v59
	v_mul_f32_e32 v72, v61, v61
	v_fmac_f32_e32 v71, v58, v58
	v_fmac_f32_e32 v72, v60, v60
	v_cvt_pk_bf16_f32 v62, v62, v63
	v_cvt_pk_bf16_f32 v63, v64, v65
	v_cvt_pk_bf16_f32 v64, v58, v59
	v_cvt_pk_bf16_f32 v65, v60, v61
	v_lshl_add_u64 v[58:59], s[82:83], 0, v[68:69]
	v_mul_f32_e32 v60, v55, v55
	v_mul_f32_e32 v61, v57, v57
	v_lshl_add_u64 v[58:59], v[58:59], 0, v[138:139]
	v_fmac_f32_e32 v60, v54, v54
	v_fmac_f32_e32 v61, v56, v56
	global_store_dwordx4 v[58:59], v[62:65], off nt
	v_add_f32_e32 v60, v60, v61
	v_mul_f32_e32 v61, v51, v51
	v_mul_f32_e32 v62, v53, v53
	v_fmac_f32_e32 v61, v50, v50
	v_fmac_f32_e32 v62, v52, v52
	v_add_f32_e32 v71, v71, v72
	v_add_f32_e32 v61, v61, v62
	v_add_f32_e32 v70, v71, v70
	v_add_f32_e32 v60, v61, v60
	v_add_f32_e32 v60, v60, v70
	v_cvt_pk_bf16_f32 v54, v54, v55
	v_cvt_pk_bf16_f32 v55, v56, v57
	v_cvt_pk_bf16_f32 v56, v50, v51
	v_mov_b32_e32 v50, v60
	s_nop 1
	v_permlane16_swap_b32_e32 v60, v50
	v_add_f32_e32 v50, v60, v50
	v_mov_b32_e32 v51, v50
	s_nop 1
	v_permlane32_swap_b32_e32 v50, v51
	v_cvt_pk_bf16_f32 v57, v52, v53
	global_store_dwordx4 v[58:59], v[54:57], off offset:256 nt
	s_and_saveexec_b64 s[34:35], s[2:3]
	s_cbranch_execz .LBB0_386
	v_add_f32_e32 v52, v50, v51
	v_lshlrev_b64 v[50:51], 6, v[66:67]
	s_lshl_b32 s10, s33, 2
	v_lshl_add_u64 v[50:51], s[20:21], 0, v[50:51]
	v_lshl_add_u64 v[50:51], s[10:11], 2, v[50:51]
	s_lshl_b32 s10, s43, 2
	v_lshl_add_u64 v[50:51], v[50:51], 0, s[10:11]
	global_store_dword v[50:51], v52, off
.LBB0_386:
	s_or_b64 exec, exec, s[34:35]
	v_add_u32_e32 v50, 0x90, v144
	v_mul_f32_e32 v54, v47, v47
	v_mul_f32_e32 v55, v49, v49
	v_ashrrev_i32_e32 v51, 31, v50
	v_fmac_f32_e32 v54, v46, v46
	v_fmac_f32_e32 v55, v48, v48
	v_lshlrev_b64 v[52:53], 11, v[50:51]
	v_add_f32_e32 v54, v54, v55
	v_mul_f32_e32 v55, v43, v43
	v_mul_f32_e32 v56, v45, v45
	v_fmac_f32_e32 v55, v42, v42
	v_fmac_f32_e32 v56, v44, v44
	v_cvt_pk_bf16_f32 v46, v46, v47
	v_cvt_pk_bf16_f32 v47, v48, v49
	v_cvt_pk_bf16_f32 v48, v42, v43
	v_cvt_pk_bf16_f32 v49, v44, v45
	v_lshl_add_u64 v[42:43], s[82:83], 0, v[52:53]
	v_mul_f32_e32 v44, v39, v39
	v_mul_f32_e32 v45, v41, v41
	v_lshl_add_u64 v[42:43], v[42:43], 0, v[138:139]
	v_fmac_f32_e32 v44, v38, v38
	v_fmac_f32_e32 v45, v40, v40
	global_store_dwordx4 v[42:43], v[46:49], off nt
	v_add_f32_e32 v44, v44, v45
	v_mul_f32_e32 v45, v35, v35
	v_mul_f32_e32 v46, v37, v37
	v_fmac_f32_e32 v45, v34, v34
	v_fmac_f32_e32 v46, v36, v36
	v_add_f32_e32 v55, v55, v56
	v_add_f32_e32 v45, v45, v46
	v_add_f32_e32 v54, v55, v54
	v_add_f32_e32 v44, v45, v44
	v_add_f32_e32 v44, v44, v54
	v_cvt_pk_bf16_f32 v38, v38, v39
	v_cvt_pk_bf16_f32 v39, v40, v41
	v_cvt_pk_bf16_f32 v40, v34, v35
	v_mov_b32_e32 v34, v44
	s_nop 1
	v_permlane16_swap_b32_e32 v44, v34
	v_add_f32_e32 v34, v44, v34
	v_mov_b32_e32 v35, v34
	s_nop 1
	v_permlane32_swap_b32_e32 v34, v35
	v_cvt_pk_bf16_f32 v41, v36, v37
	global_store_dwordx4 v[42:43], v[38:41], off offset:256 nt
	s_and_saveexec_b64 s[34:35], s[2:3]
	s_cbranch_execz .LBB0_388
	v_add_f32_e32 v36, v34, v35
	v_lshlrev_b64 v[34:35], 6, v[50:51]
	s_lshl_b32 s10, s33, 2
	v_lshl_add_u64 v[34:35], s[20:21], 0, v[34:35]
	v_lshl_add_u64 v[34:35], s[10:11], 2, v[34:35]
	s_lshl_b32 s10, s43, 2
	v_lshl_add_u64 v[34:35], v[34:35], 0, s[10:11]
	global_store_dword v[34:35], v36, off
.LBB0_388:
	s_or_b64 exec, exec, s[34:35]
	v_add_u32_e32 v34, 0xa0, v144
	v_mul_f32_e32 v38, v31, v31
	v_mul_f32_e32 v39, v33, v33
	v_ashrrev_i32_e32 v35, 31, v34
	v_fmac_f32_e32 v38, v30, v30
	v_fmac_f32_e32 v39, v32, v32
	v_lshlrev_b64 v[36:37], 11, v[34:35]
	v_add_f32_e32 v38, v38, v39
	v_mul_f32_e32 v39, v27, v27
	v_mul_f32_e32 v40, v29, v29
	v_fmac_f32_e32 v39, v26, v26
	v_fmac_f32_e32 v40, v28, v28
	v_cvt_pk_bf16_f32 v30, v30, v31
	v_cvt_pk_bf16_f32 v31, v32, v33
	v_cvt_pk_bf16_f32 v32, v26, v27
	v_cvt_pk_bf16_f32 v33, v28, v29
	v_lshl_add_u64 v[26:27], s[82:83], 0, v[36:37]
	v_mul_f32_e32 v28, v23, v23
	v_mul_f32_e32 v29, v25, v25
	v_lshl_add_u64 v[26:27], v[26:27], 0, v[138:139]
	v_fmac_f32_e32 v28, v22, v22
	v_fmac_f32_e32 v29, v24, v24
	global_store_dwordx4 v[26:27], v[30:33], off nt
	v_add_f32_e32 v28, v28, v29
	v_mul_f32_e32 v29, v19, v19
	v_mul_f32_e32 v30, v21, v21
	v_fmac_f32_e32 v29, v18, v18
	v_fmac_f32_e32 v30, v20, v20
	v_add_f32_e32 v39, v39, v40
	v_add_f32_e32 v29, v29, v30
	v_add_f32_e32 v38, v39, v38
	v_add_f32_e32 v28, v29, v28
	v_add_f32_e32 v28, v28, v38
	v_cvt_pk_bf16_f32 v22, v22, v23
	v_cvt_pk_bf16_f32 v23, v24, v25
	v_cvt_pk_bf16_f32 v24, v18, v19
	v_mov_b32_e32 v18, v28
	s_nop 1
	v_permlane16_swap_b32_e32 v28, v18
	v_add_f32_e32 v18, v28, v18
	v_mov_b32_e32 v19, v18
	s_nop 1
	v_permlane32_swap_b32_e32 v18, v19
	v_cvt_pk_bf16_f32 v25, v20, v21
	global_store_dwordx4 v[26:27], v[22:25], off offset:256 nt
	s_and_saveexec_b64 s[34:35], s[2:3]
	s_cbranch_execz .LBB0_390
	v_add_f32_e32 v20, v18, v19
	v_lshlrev_b64 v[18:19], 6, v[34:35]
	s_lshl_b32 s10, s33, 2
	v_lshl_add_u64 v[18:19], s[20:21], 0, v[18:19]
	v_lshl_add_u64 v[18:19], s[10:11], 2, v[18:19]
	s_lshl_b32 s10, s43, 2
	v_lshl_add_u64 v[18:19], v[18:19], 0, s[10:11]
	global_store_dword v[18:19], v20, off
.LBB0_390:
	s_or_b64 exec, exec, s[34:35]
	v_add_u32_e32 v18, 0xb0, v144
	v_mul_f32_e32 v22, v15, v15
	v_mul_f32_e32 v23, v17, v17
	v_ashrrev_i32_e32 v19, 31, v18
	v_fmac_f32_e32 v22, v14, v14
	v_fmac_f32_e32 v23, v16, v16
	v_lshlrev_b64 v[20:21], 11, v[18:19]
	v_add_f32_e32 v22, v22, v23
	v_mul_f32_e32 v23, v11, v11
	v_mul_f32_e32 v24, v13, v13
	v_fmac_f32_e32 v23, v10, v10
	v_fmac_f32_e32 v24, v12, v12
	v_cvt_pk_bf16_f32 v14, v14, v15
	v_cvt_pk_bf16_f32 v15, v16, v17
	v_cvt_pk_bf16_f32 v16, v10, v11
	v_cvt_pk_bf16_f32 v17, v12, v13
	v_lshl_add_u64 v[10:11], s[82:83], 0, v[20:21]
	v_mul_f32_e32 v12, v7, v7
	v_mul_f32_e32 v13, v9, v9
	v_lshl_add_u64 v[10:11], v[10:11], 0, v[138:139]
	v_fmac_f32_e32 v12, v6, v6
	v_fmac_f32_e32 v13, v8, v8
	global_store_dwordx4 v[10:11], v[14:17], off nt
	v_add_f32_e32 v12, v12, v13
	v_mul_f32_e32 v13, v3, v3
	v_mul_f32_e32 v14, v5, v5
	v_fmac_f32_e32 v13, v2, v2
	v_fmac_f32_e32 v14, v4, v4
	v_add_f32_e32 v23, v23, v24
	v_add_f32_e32 v13, v13, v14
	v_add_f32_e32 v22, v23, v22
	v_add_f32_e32 v12, v13, v12
	v_add_f32_e32 v12, v12, v22
	v_cvt_pk_bf16_f32 v6, v6, v7
	v_cvt_pk_bf16_f32 v7, v8, v9
	v_cvt_pk_bf16_f32 v8, v2, v3
	v_mov_b32_e32 v2, v12
	s_nop 1
	v_permlane16_swap_b32_e32 v12, v2
	v_add_f32_e32 v2, v12, v2
	v_mov_b32_e32 v3, v2
	s_nop 1
	v_permlane32_swap_b32_e32 v2, v3
	v_cvt_pk_bf16_f32 v9, v4, v5
	global_store_dwordx4 v[10:11], v[6:9], off offset:256 nt
	s_and_saveexec_b64 s[34:35], s[2:3]
	s_cbranch_execz .LBB0_392
	v_add_f32_e32 v4, v2, v3
	v_lshlrev_b64 v[2:3], 6, v[18:19]
	s_lshl_b32 s10, s33, 2
	v_lshl_add_u64 v[2:3], s[20:21], 0, v[2:3]
	v_lshl_add_u64 v[2:3], s[10:11], 2, v[2:3]
	s_lshl_b32 s10, s43, 2
	v_lshl_add_u64 v[2:3], v[2:3], 0, s[10:11]
	global_store_dword v[2:3], v4, off
